# stack on v44: convA halo loads de-serialized, FFN1 first-iteration vmcnt relax past epilogue stores, packed-f32 SwiGLU epilogue, packed-f32 SSD decay-matrix blocks
# speedup vs baseline: 1.0077x; 1.0077x over previous
; __device__ __forceinline__ u32x4 pack8(const float (&o)[8]) { u32x4 r; r.x = pk2(o[0], o[1]); r.y = pk2(o[2], o[3]); r.z = pk2(o[4], o[5]); r.w = pk2(o[6], o[7]); return r; }
; __device__ __forceinline__ void phase_ssd(const Params& p, uchar* sm, int j, bf16_t* zx, const float* dtraw, float* ssqb) {
;     ...
;                 const int mq = w & 3; const int l = mq * 16 + l15; const float csl = csL[rl * 64 + l];
; #pragma unroll
;                 for (int ks = 0; ks < 2; ++ks) {
;                     if (ks == 1 && mq < 2) continue;
;                     const f32x4 s0 = *(const f32x4*)(csL + rl * 64 + ks * 32 + quad * 8), s1 = *(const f32x4*)(csL + rl * 64 + ks * 32 + quad * 8 + 4);
;                     const f32x4 c0 = *(const f32x4*)(sm + L_CB + l * RS_CB + (ks * 32 + quad * 8) * 4), c1 = *(const f32x4*)(sm + L_CB + l * RS_CB + (ks * 32 + quad * 8 + 4) * 4);
;                     float mv[8];
; #pragma unroll
;                     for (int i = 0; i < 4; ++i) { const int sc = ks * 32 + quad * 8 + i;
;                         mv[i] = (sc <= l) ? c0[i] * __expf(csl - s0[i]) : 0.f;
;                         mv[4 + i] = (sc + 4 <= l) ? c1[i] * __expf(csl - s1[i]) : 0.f; }
;                     *(u32x4*)(sm + LDS_MM + (rl * 64 + l) * RS_T + (ks * 32 + quad * 8) * 2) = pack8(mv);
;                 }
.LBB0_475:
	s_or_b64 exec, exec, s[4:5]
	s_mov_b64 s[4:5], 0x641c000
	v_lshl_add_u64 v[180:181], v[104:105], 0, s[4:5]
	s_mov_b64 s[4:5], 0x641f080
	v_lshl_add_u64 v[178:179], v[104:105], 0, s[4:5]
	s_waitcnt lgkmcnt(0)
	s_barrier
	ds_read_b32 v104, v193
	ds_read_b128 v[106:109], v196
	ds_read_b128 v[110:113], v196 offset:16
	v_add_u32_e32 v105, v197, v195
	ds_read_b128 v[114:117], v105
	ds_read_b128 v[118:121], v105 offset:16
	s_waitcnt lgkmcnt(2)
	v_pk_add_f32 v[106:107], v[106:107], v[104:105] op_sel_hi:[1,0] neg_lo:[0,1] neg_hi:[0,1]
	v_pk_add_f32 v[108:109], v[108:109], v[104:105] op_sel_hi:[1,0] neg_lo:[0,1] neg_hi:[0,1]
	v_pk_add_f32 v[110:111], v[110:111], v[104:105] op_sel_hi:[1,0] neg_lo:[0,1] neg_hi:[0,1]
	v_pk_add_f32 v[112:113], v[112:113], v[104:105] op_sel_hi:[1,0] neg_lo:[0,1] neg_hi:[0,1]
	v_pk_mul_f32 v[106:107], v[106:107], s[98:99]
	v_pk_mul_f32 v[108:109], v[108:109], s[98:99]
	v_pk_mul_f32 v[110:111], v[110:111], s[98:99]
	v_pk_mul_f32 v[112:113], v[112:113], s[98:99]
	v_exp_f32_e32 v106, v106
	v_exp_f32_e32 v107, v107
	v_exp_f32_e32 v108, v108
	v_exp_f32_e32 v109, v109
	v_exp_f32_e32 v110, v110
	v_exp_f32_e32 v111, v111
	v_exp_f32_e32 v112, v112
	v_exp_f32_e32 v113, v113
	s_waitcnt lgkmcnt(0)
	v_pk_mul_f32 v[106:107], v[114:115], v[106:107]
	v_pk_mul_f32 v[108:109], v[116:117], v[108:109]
	v_pk_mul_f32 v[110:111], v[118:119], v[110:111]
	v_pk_mul_f32 v[112:113], v[120:121], v[112:113]
	v_cndmask_b32_e64 v106, v106, 0, s[26:27]
	v_cndmask_b32_e64 v107, 0, v107, s[30:31]
	v_cndmask_b32_e64 v108, v108, 0, s[36:37]
	v_cndmask_b32_e64 v109, v109, 0, s[40:41]
	v_cndmask_b32_e64 v110, v110, 0, s[28:29]
	v_cndmask_b32_e64 v111, v111, 0, s[34:35]
	v_cndmask_b32_e64 v112, v112, 0, s[38:39]
	v_cndmask_b32_e64 v113, v113, 0, s[42:43]
	v_add_u32_e32 v105, v198, v188
	v_cvt_pk_bf16_f32 v106, v106, v107
	v_cvt_pk_bf16_f32 v107, v108, v109
	v_cvt_pk_bf16_f32 v108, v110, v111
	v_cvt_pk_bf16_f32 v109, v112, v113
	ds_write_b128 v105, v[106:109]
	s_and_saveexec_b64 s[4:5], s[22:23]
	s_cbranch_execz .LBB0_477
	ds_read_b128 v[106:109], v196 offset:128
	ds_read_b128 v[110:113], v196 offset:144
	ds_read_b128 v[114:117], v214
	ds_read_b128 v[118:121], v214 offset:16
	s_waitcnt lgkmcnt(2)
	v_pk_add_f32 v[106:107], v[106:107], v[104:105] op_sel_hi:[1,0] neg_lo:[0,1] neg_hi:[0,1]
	v_pk_add_f32 v[108:109], v[108:109], v[104:105] op_sel_hi:[1,0] neg_lo:[0,1] neg_hi:[0,1]
	v_pk_add_f32 v[110:111], v[110:111], v[104:105] op_sel_hi:[1,0] neg_lo:[0,1] neg_hi:[0,1]
	v_pk_add_f32 v[112:113], v[112:113], v[104:105] op_sel_hi:[1,0] neg_lo:[0,1] neg_hi:[0,1]
	v_pk_mul_f32 v[106:107], v[106:107], s[98:99]
	v_pk_mul_f32 v[108:109], v[108:109], s[98:99]
	v_pk_mul_f32 v[110:111], v[110:111], s[98:99]
	v_pk_mul_f32 v[112:113], v[112:113], s[98:99]
	v_exp_f32_e32 v106, v106
	v_exp_f32_e32 v107, v107
	v_exp_f32_e32 v108, v108
	v_exp_f32_e32 v109, v109
	v_exp_f32_e32 v110, v110
	v_exp_f32_e32 v111, v111
	v_exp_f32_e32 v112, v112
	v_exp_f32_e32 v113, v113
	s_waitcnt lgkmcnt(0)
	v_pk_mul_f32 v[106:107], v[114:115], v[106:107]
	v_pk_mul_f32 v[108:109], v[116:117], v[108:109]
	v_pk_mul_f32 v[110:111], v[118:119], v[110:111]
	v_pk_mul_f32 v[112:113], v[120:121], v[112:113]
	v_cndmask_b32_e64 v106, v106, 0, s[44:45]
	v_cndmask_b32_e64 v107, v107, 0, s[48:49]
	v_cndmask_b32_e64 v108, v108, 0, s[52:53]
	v_cndmask_b32_e64 v109, v109, 0, s[56:57]
	v_cndmask_b32_e64 v110, v110, 0, s[46:47]
	v_cndmask_b32_e64 v111, v111, 0, s[50:51]
	v_cndmask_b32_e64 v112, v112, 0, s[54:55]
	v_cndmask_b32_e64 v113, v113, 0, s[58:59]
	v_cvt_pk_bf16_f32 v104, v106, v107
	v_cvt_pk_bf16_f32 v105, v108, v109
	v_cvt_pk_bf16_f32 v106, v110, v111
	v_cvt_pk_bf16_f32 v107, v112, v113
	ds_write_b128 v215, v[104:107]

; __device__ __forceinline__ void phase_convA(const Params& p, const bf16_t* bcv  , bf16_t* tout, const float* cw  ) {
;     ...
;         float w0[8], w1[8], w2[8];
; #pragma unroll
;         for (int h = 0; h < 2; ++h) { const f32x4 a = *(const f32x4*)(cw + c8 * 8 + h * 4), b = *(const f32x4*)(cw + 1024 + c8 * 8 + h * 4), c = *(const f32x4*)(cw + 2048 + c8 * 8 + h * 4);
; #pragma unroll
;             for (int i = 0; i < 4; ++i) { w0[h * 4 + i] = a[i]; w1[h * 4 + i] = b[i]; w2[h * 4 + i] = c[i]; } }
;         const size_t r0 = (size_t)rg * 16;
;         float cvm2[8], cvm1[8];
; #pragma unroll
;         for (int i = 0; i < 8; ++i) { cvm2[i] = 0.f; cvm1[i] = 0.f; }
;         if ((r0 & 2047) != 0) {
;             unpack8(*(const u32x4*)(bcv + (r0 - 2) * 2048 + 1024 + c8 * 8), cvm2);
;             unpack8(*(const u32x4*)(bcv + (r0 - 1) * 2048 + 1024 + c8 * 8), cvm1);
;         }
.LBB0_748:
	global_load_dwordx4 v[2:5], v[90:91], off offset:16
	global_load_dwordx4 v[14:17], v[90:91], off
	global_load_dwordx4 v[10:13], v[92:93], off offset:16
	global_load_dwordx4 v[22:25], v[92:93], off
	global_load_dwordx4 v[6:9], v[94:95], off offset:16
	global_load_dwordx4 v[18:21], v[94:95], off
	v_ashrrev_i32_e32 v28, 7, v1
	v_ashrrev_i32_e32 v29, 31, v28
	v_and_b32_e32 v26, 0x3f80, v1
	v_cmp_ne_u32_e32 vcc, 0, v26
	v_lshlrev_b64 v[26:27], 16, v[28:29]
	v_mov_b32_e32 v66, 0
	v_mov_b32_e32 v68, 0
	v_mov_b32_e32 v70, 0
	v_mov_b32_e32 v72, 0
	v_mov_b32_e32 v74, 0
	v_mov_b32_e32 v76, 0
	v_mov_b32_e32 v82, 0
	v_mov_b32_e32 v122, 0
	v_mov_b32_e32 v83, 0
	v_mov_b32_e32 v77, 0
	v_mov_b32_e32 v75, 0
	v_mov_b32_e32 v73, 0
	v_mov_b32_e32 v71, 0
	v_mov_b32_e32 v69, 0
	v_mov_b32_e32 v67, 0
	v_mov_b32_e32 v101, 0
	s_and_saveexec_b64 s[6:7], vcc
	s_cbranch_execz .LBB0_747
	v_lshl_add_u64 v[30:31], s[90:91], 0, v[26:27]
	v_mov_b32_e32 v101, v0
	v_lshl_add_u64 v[34:35], v[30:31], 0, v[100:101]
	v_add_co_u32_e32 v30, vcc, 0xfffff000, v34
	s_nop 1
	v_addc_co_u32_e32 v31, vcc, -1, v35, vcc
	global_load_dwordx4 v[30:33], v[30:31], off offset:-2048
	global_load_dwordx4 v[124:127], v[34:35], off offset:-2048
	s_waitcnt vmcnt(0)
	v_lshlrev_b32_e32 v122, 16, v30
	v_and_b32_e32 v82, 0xffff0000, v30
	v_lshlrev_b32_e32 v76, 16, v31
	v_and_b32_e32 v74, 0xffff0000, v31
	v_lshlrev_b32_e32 v72, 16, v32
	v_and_b32_e32 v70, 0xffff0000, v32
	v_lshlrev_b32_e32 v68, 16, v33
	v_and_b32_e32 v66, 0xffff0000, v33
	v_lshlrev_b32_e32 v83, 16, v124
	v_and_b32_e32 v77, 0xffff0000, v124
	v_lshlrev_b32_e32 v75, 16, v125
	v_and_b32_e32 v73, 0xffff0000, v125
	v_lshlrev_b32_e32 v71, 16, v126
	v_and_b32_e32 v69, 0xffff0000, v126
	v_lshlrev_b32_e32 v67, 16, v127
	v_and_b32_e32 v101, 0xffff0000, v127
	s_branch .LBB0_747

; #define PG8_STAGE(bufoff, gbase, voff) do { _Pragma("unroll") for (int _i = 0; _i < 2; ++_i) \
;         __builtin_amdgcn_global_load_lds((const unsigned*)((const char*)(gbase) + (voff)[_i]), (LAS unsigned*)(lds + (bufoff) + ldsw + _i * 8192), 16, 0, 0); } while (0)
; #define PG8_LDA(dst, b, h) do { _Pragma("unroll") for (int m = 0; m < 4; ++m) _Pragma("unroll") for (int k = 0; k < 2; ++k) dst[m][k] = *(const LAS bf16x8*)(lds + PG8_SA(b, h) + aoff + m * 2048 + k * 1024); } while (0)
; #define PG8_LDB(dst, b, h) do { _Pragma("unroll") for (int n = 0; n < 2; ++n) _Pragma("unroll") for (int k = 0; k < 2; ++k) dst[n][k] = *(const LAS bf16x8*)(lds + PG8_SB(b, h) + boff + n * 2048 + k * 1024); } while (0)
; #define PG8_MMA(ai, bj, At, Bt) do { __builtin_amdgcn_s_setprio(1); _Pragma("unroll") for (int m = 0; m < 4; ++m) _Pragma("unroll") for (int n = 0; n < 2; ++n) _Pragma("unroll") for (int k = 0; k < 2; ++k) \
;         acc[ai][bj][m][n] = __builtin_amdgcn_mfma_f32_16x16x32_bf16(Bt[n][k], At[m][k], acc[ai][bj][m][n], 0, 0, 0); __builtin_amdgcn_s_setprio(0); } while (0)
; #define PG8_WAIT_V(n) asm volatile("s_waitcnt vmcnt(" #n ")" ::: "memory")
; template <class Epi, bool ALIGN_EPI = PG8_ALIGN, bool SP2 = PG8_SP2>
; __device__ __forceinline__ void gemm_phase(LAS uchar* lds, const Gemm g, const StaticOrder& S, const Epi& E) {
;     ...
;         for (int t = tb; t < tb + tblk; t += 2) {
;             const bool last = (t == nt - 2);
;             const char* a1 = cA + (size_t)(t + 1) * kstep;
;             const char* a2 = last ? nA : cA + (size_t)(t + 2) * kstep; const char* b2 = last ? nB : cB + (size_t)(t + 2) * kstep;
;             const char* a3 = a2 + kstep; const char* b3 = b2 + kstep;
;             if constexpr (SP2) {
;             PG8_LDB(B0, 0, 0); PG8_LDB(B1, 0, 1); PG8_SCHED; PG8_LDA(At, 0, 0); PG8_STAGE(PG8_SA(1, 1), a1 + hstepA, voffA);
;             PG8_WAIT_V(8); PG8_WAIT_L(0); PG8_BAR; PG8_MMA(0, 0, At, B0); PG8_MMA(0, 1, At, B1); PG8_BAR; PG8_SCHED;
;             PG8_LDA(At, 0, 1); PG8_STAGE(PG8_SB(0, 0), b2, voffB); PG8_STAGE(PG8_SB(0, 1), b2 + hstepB, voffB); PG8_STAGE(PG8_SA(0, 0), a2, voffA);
;             PG8_WAIT_V(8); PG8_WAIT_L(0); PG8_BAR; PG8_MMA(1, 0, At, B0); PG8_MMA(1, 1, At, B1); PG8_BAR; PG8_SCHED;
;             PG8_LDB(B0, 1, 0); PG8_LDB(B1, 1, 1); PG8_SCHED; PG8_LDA(At, 1, 0); PG8_STAGE(PG8_SA(0, 1), a2 + hstepA, voffA);
.LBB0_1050:
	s_add_u32 s14, s12, 0x100
	s_addc_u32 s15, s13, 0
	s_add_i32 s39, 0, 0x10000
	s_cmp_eq_u32 s38, 12
	s_cselect_b32 s19, s1, s15
	s_cselect_b32 s18, s0, s14
	v_add_u32_e32 v144, s39, v139
	s_cselect_b32 s17, s11, s37
	s_cselect_b32 s16, s10, s36
	s_add_i32 s40, 0, 0x14000
	ds_read_b128 v[164:167], v144
	ds_read_b128 v[168:171], v144 offset:1024
	ds_read_b128 v[172:175], v144 offset:2048
	ds_read_b128 v[176:179], v144 offset:3072
	v_add_u32_e32 v144, s40, v139
	ds_read_b128 v[184:187], v144
	ds_read_b128 v[188:191], v144 offset:1024
	ds_read_b128 v[192:195], v144 offset:2048
	ds_read_b128 v[196:199], v144 offset:3072
	v_lshl_add_u64 v[160:161], s[12:13], 0, v[156:157]
	s_add_i32 m0, s23, 0xc000
	ds_read_b128 v[200:203], v163
	ds_read_b128 v[204:207], v163 offset:1024
	ds_read_b128 v[208:211], v163 offset:2048
	ds_read_b128 v[212:215], v163 offset:3072
	ds_read_b128 v[216:219], v163 offset:4096
	ds_read_b128 v[220:223], v163 offset:5120
	ds_read_b128 v[224:227], v163 offset:6144
	ds_read_b128 v[228:231], v163 offset:7168
	global_load_lds_dwordx4 v[160:161], off
	v_lshl_add_u64 v[160:161], s[12:13], 0, v[158:159]
	s_add_i32 m0, s23, 0xe000
	s_nop 0
	global_load_lds_dwordx4 v[160:161], off
	s_cmp_lt_i32 s38, 0
	s_cbranch_scc0 .Lrw_std_1050_0
	s_cmp_lt_u32 s29, 2
	s_cbranch_scc1 .Lrw_std_1050_0
	s_waitcnt vmcnt(16)
	s_branch .Lrw_done_1050_0
.Lrw_std_1050_0:
	s_waitcnt vmcnt(8)
.Lrw_done_1050_0:
	s_waitcnt lgkmcnt(0)
	s_barrier
	s_setprio 1
	s_waitcnt lgkmcnt(0)
	v_mfma_f32_16x16x32_bf16 v[126:129], v[164:167], v[200:203], v[126:129]
	v_mfma_f32_16x16x32_bf16 v[118:121], v[172:175], v[200:203], v[118:121]
	v_mfma_f32_16x16x32_bf16 v[110:113], v[164:167], v[208:211], v[110:113]
	v_mfma_f32_16x16x32_bf16 v[102:105], v[172:175], v[208:211], v[102:105]
	v_mfma_f32_16x16x32_bf16 v[94:97], v[164:167], v[216:219], v[94:97]
	v_mfma_f32_16x16x32_bf16 v[86:89], v[172:175], v[216:219], v[86:89]
	v_mfma_f32_16x16x32_bf16 v[78:81], v[164:167], v[224:227], v[78:81]
	v_mfma_f32_16x16x32_bf16 v[70:73], v[172:175], v[224:227], v[70:73]
	v_mfma_f32_16x16x32_bf16 v[126:129], v[168:171], v[204:207], v[126:129]
	v_mfma_f32_16x16x32_bf16 v[118:121], v[176:179], v[204:207], v[118:121]
	v_mfma_f32_16x16x32_bf16 v[110:113], v[168:171], v[212:215], v[110:113]
	v_mfma_f32_16x16x32_bf16 v[102:105], v[176:179], v[212:215], v[102:105]
	v_mfma_f32_16x16x32_bf16 v[94:97], v[168:171], v[220:223], v[94:97]
	v_mfma_f32_16x16x32_bf16 v[86:89], v[176:179], v[220:223], v[86:89]
	v_mfma_f32_16x16x32_bf16 v[78:81], v[168:171], v[228:231], v[78:81]
	v_mfma_f32_16x16x32_bf16 v[70:73], v[176:179], v[228:231], v[70:73]
	s_setprio 0
	s_setprio 1
	v_mfma_f32_16x16x32_bf16 v[122:125], v[184:187], v[200:203], v[122:125]
	v_mfma_f32_16x16x32_bf16 v[114:117], v[192:195], v[200:203], v[114:117]
	v_mfma_f32_16x16x32_bf16 v[106:109], v[184:187], v[208:211], v[106:109]
	v_mfma_f32_16x16x32_bf16 v[98:101], v[192:195], v[208:211], v[98:101]
	v_mfma_f32_16x16x32_bf16 v[90:93], v[184:187], v[216:219], v[90:93]
	v_mfma_f32_16x16x32_bf16 v[82:85], v[192:195], v[216:219], v[82:85]
	v_mfma_f32_16x16x32_bf16 v[74:77], v[184:187], v[224:227], v[74:77]
	v_mfma_f32_16x16x32_bf16 v[66:69], v[192:195], v[224:227], v[66:69]
	v_mfma_f32_16x16x32_bf16 v[122:125], v[188:191], v[204:207], v[122:125]
	v_mfma_f32_16x16x32_bf16 v[114:117], v[196:199], v[204:207], v[114:117]
	v_mfma_f32_16x16x32_bf16 v[106:109], v[188:191], v[212:215], v[106:109]
	v_mfma_f32_16x16x32_bf16 v[98:101], v[196:199], v[212:215], v[98:101]
	v_mfma_f32_16x16x32_bf16 v[90:93], v[188:191], v[220:223], v[90:93]
	v_mfma_f32_16x16x32_bf16 v[82:85], v[196:199], v[220:223], v[82:85]
	v_mfma_f32_16x16x32_bf16 v[74:77], v[188:191], v[228:231], v[74:77]
	v_mfma_f32_16x16x32_bf16 v[66:69], v[196:199], v[228:231], v[66:69]
	s_setprio 0
	s_barrier
	s_add_i32 s12, s39, s21
	v_lshl_add_u64 v[160:161], s[16:17], 0, v[134:135]
	s_mov_b32 m0, s12
	ds_read_b128 v[200:203], v163 offset:16384
	ds_read_b128 v[204:207], v163 offset:17408
	ds_read_b128 v[208:211], v163 offset:18432
	ds_read_b128 v[212:215], v163 offset:19456
	ds_read_b128 v[216:219], v163 offset:20480
	ds_read_b128 v[220:223], v163 offset:21504
	ds_read_b128 v[224:227], v163 offset:22528
	ds_read_b128 v[228:231], v163 offset:23552
	global_load_lds_dwordx4 v[160:161], off
	s_add_i32 m0, s12, 0x2000
	s_add_u32 s12, s16, 0x44000
	v_lshl_add_u64 v[180:181], s[16:17], 0, v[130:131]
	s_addc_u32 s13, s17, 0
	s_add_i32 s39, s40, s21
	global_load_lds_dwordx4 v[180:181], off
	v_lshl_add_u64 v[232:233], s[12:13], 0, v[134:135]
	s_mov_b32 m0, s39
	v_lshl_add_u64 v[234:235], s[18:19], 0, v[132:133]
	global_load_lds_dwordx4 v[232:233], off
	v_lshl_add_u64 v[232:233], s[12:13], 0, v[130:131]
	s_add_i32 m0, s39, 0x2000
	s_nop 0
	global_load_lds_dwordx4 v[232:233], off
	v_lshl_add_u64 v[232:233], s[18:19], 0, v[154:155]
	s_mov_b32 m0, s23
	s_nop 0
	global_load_lds_dwordx4 v[232:233], off
	s_mov_b32 m0, s24
	s_nop 0
	global_load_lds_dwordx4 v[234:235], off
	s_cmp_lt_i32 s38, 0
	s_cbranch_scc0 .Lrw_std_1050_1
	s_cmp_lt_u32 s29, 2
	s_cbranch_scc1 .Lrw_std_1050_1
	s_waitcnt vmcnt(16)
	s_branch .Lrw_done_1050_1

; #define PG8_STAGE(bufoff, gbase, voff) do { _Pragma("unroll") for (int _i = 0; _i < 2; ++_i) \
;         __builtin_amdgcn_global_load_lds((const unsigned*)((const char*)(gbase) + (voff)[_i]), (LAS unsigned*)(lds + (bufoff) + ldsw + _i * 8192), 16, 0, 0); } while (0)
; #define PG8_LDA(dst, b, h) do { _Pragma("unroll") for (int m = 0; m < 4; ++m) _Pragma("unroll") for (int k = 0; k < 2; ++k) dst[m][k] = *(const LAS bf16x8*)(lds + PG8_SA(b, h) + aoff + m * 2048 + k * 1024); } while (0)
; #define PG8_LDB(dst, b, h) do { _Pragma("unroll") for (int n = 0; n < 2; ++n) _Pragma("unroll") for (int k = 0; k < 2; ++k) dst[n][k] = *(const LAS bf16x8*)(lds + PG8_SB(b, h) + boff + n * 2048 + k * 1024); } while (0)
; #define PG8_MMA(ai, bj, At, Bt) do { __builtin_amdgcn_s_setprio(1); _Pragma("unroll") for (int m = 0; m < 4; ++m) _Pragma("unroll") for (int n = 0; n < 2; ++n) _Pragma("unroll") for (int k = 0; k < 2; ++k) \
;         acc[ai][bj][m][n] = __builtin_amdgcn_mfma_f32_16x16x32_bf16(Bt[n][k], At[m][k], acc[ai][bj][m][n], 0, 0, 0); __builtin_amdgcn_s_setprio(0); } while (0)
; #define PG8_WAIT_V(n) asm volatile("s_waitcnt vmcnt(" #n ")" ::: "memory")
; #define PG8_WAIT_L(n) asm volatile("s_waitcnt lgkmcnt(" #n ")" ::: "memory")
; #define PG8_BAR __builtin_amdgcn_s_barrier()
; #define PG8_SCHED __builtin_amdgcn_sched_barrier(0)
; template <class Epi, bool ALIGN_EPI = PG8_ALIGN, bool SP2 = PG8_SP2>
; __device__ __forceinline__ void gemm_phase(LAS uchar* lds, const Gemm g, const StaticOrder& S, const Epi& E) {
;     ...
;             PG8_WAIT_V(8); PG8_WAIT_L(0); PG8_BAR; PG8_MMA(0, 0, At, B0); PG8_MMA(0, 1, At, B1); PG8_BAR; PG8_SCHED;
;             PG8_LDA(At, 0, 1); PG8_STAGE(PG8_SB(0, 0), b2, voffB); PG8_STAGE(PG8_SB(0, 1), b2 + hstepB, voffB); PG8_STAGE(PG8_SA(0, 0), a2, voffA);
;             PG8_WAIT_V(8); PG8_WAIT_L(0); PG8_BAR; PG8_MMA(1, 0, At, B0); PG8_MMA(1, 1, At, B1); PG8_BAR; PG8_SCHED;
;             PG8_LDB(B0, 1, 0); PG8_LDB(B1, 1, 1); PG8_SCHED; PG8_LDA(At, 1, 0); PG8_STAGE(PG8_SA(0, 1), a2 + hstepA, voffA);
;             PG8_WAIT_V(8); PG8_WAIT_L(0); PG8_BAR; PG8_MMA(0, 0, At, B0); PG8_MMA(0, 1, At, B1); PG8_BAR; PG8_SCHED;
.Lrw_done_1050_1:
	s_waitcnt lgkmcnt(0)
	s_barrier
	s_setprio 1
	s_waitcnt lgkmcnt(0)
	v_mfma_f32_16x16x32_bf16 v[62:65], v[164:167], v[200:203], v[62:65]
	v_mfma_f32_16x16x32_bf16 v[54:57], v[172:175], v[200:203], v[54:57]
	v_mfma_f32_16x16x32_bf16 v[46:49], v[164:167], v[208:211], v[46:49]
	v_mfma_f32_16x16x32_bf16 v[38:41], v[172:175], v[208:211], v[38:41]
	v_mfma_f32_16x16x32_bf16 v[30:33], v[164:167], v[216:219], v[30:33]
	v_mfma_f32_16x16x32_bf16 v[22:25], v[172:175], v[216:219], v[22:25]
	v_mfma_f32_16x16x32_bf16 v[14:17], v[164:167], v[224:227], v[14:17]
	v_mfma_f32_16x16x32_bf16 v[6:9], v[172:175], v[224:227], v[6:9]
	v_mfma_f32_16x16x32_bf16 v[62:65], v[168:171], v[204:207], v[62:65]
	v_mfma_f32_16x16x32_bf16 v[54:57], v[176:179], v[204:207], v[54:57]
	v_mfma_f32_16x16x32_bf16 v[46:49], v[168:171], v[212:215], v[46:49]
	v_mfma_f32_16x16x32_bf16 v[38:41], v[176:179], v[212:215], v[38:41]
	v_mfma_f32_16x16x32_bf16 v[30:33], v[168:171], v[220:223], v[30:33]
	v_mfma_f32_16x16x32_bf16 v[22:25], v[176:179], v[220:223], v[22:25]
	v_mfma_f32_16x16x32_bf16 v[14:17], v[168:171], v[228:231], v[14:17]
	v_mfma_f32_16x16x32_bf16 v[6:9], v[176:179], v[228:231], v[6:9]
	s_setprio 0
	s_setprio 1
	v_mfma_f32_16x16x32_bf16 v[58:61], v[184:187], v[200:203], v[58:61]
	v_mfma_f32_16x16x32_bf16 v[50:53], v[192:195], v[200:203], v[50:53]
	v_mfma_f32_16x16x32_bf16 v[42:45], v[184:187], v[208:211], v[42:45]
	v_mfma_f32_16x16x32_bf16 v[34:37], v[192:195], v[208:211], v[34:37]
	v_mfma_f32_16x16x32_bf16 v[26:29], v[184:187], v[216:219], v[26:29]
	v_mfma_f32_16x16x32_bf16 v[18:21], v[192:195], v[216:219], v[18:21]
	v_mfma_f32_16x16x32_bf16 v[10:13], v[184:187], v[224:227], v[10:13]
	v_mfma_f32_16x16x32_bf16 v[2:5], v[192:195], v[224:227], v[2:5]
	v_mfma_f32_16x16x32_bf16 v[58:61], v[188:191], v[204:207], v[58:61]
	v_mfma_f32_16x16x32_bf16 v[50:53], v[196:199], v[204:207], v[50:53]
	v_mfma_f32_16x16x32_bf16 v[42:45], v[188:191], v[212:215], v[42:45]
	v_mfma_f32_16x16x32_bf16 v[34:37], v[196:199], v[212:215], v[34:37]
	v_mfma_f32_16x16x32_bf16 v[26:29], v[188:191], v[220:223], v[26:29]
	v_mfma_f32_16x16x32_bf16 v[18:21], v[196:199], v[220:223], v[18:21]
	v_mfma_f32_16x16x32_bf16 v[10:13], v[188:191], v[228:231], v[10:13]
	v_mfma_f32_16x16x32_bf16 v[2:5], v[196:199], v[228:231], v[2:5]
	s_setprio 0
	s_barrier
	s_add_i32 s39, 0, 0x18000
	v_add_u32_e32 v144, s39, v139
	s_add_i32 s40, 0, 0x1c000
	ds_read_b128 v[164:167], v144
	ds_read_b128 v[168:171], v144 offset:1024
	ds_read_b128 v[172:175], v144 offset:2048
	ds_read_b128 v[176:179], v144 offset:3072
	v_add_u32_e32 v144, s40, v139
	ds_read_b128 v[184:187], v144
	ds_read_b128 v[188:191], v144 offset:1024
	ds_read_b128 v[192:195], v144 offset:2048
	ds_read_b128 v[196:199], v144 offset:3072
	s_add_u32 s12, s18, 0x44000
	s_addc_u32 s13, s19, 0
	s_mov_b32 m0, s25
	v_lshl_add_u64 v[236:237], s[12:13], 0, v[154:155]
	ds_read_b128 v[200:203], v163 offset:32768
	ds_read_b128 v[204:207], v163 offset:33792
	ds_read_b128 v[208:211], v163 offset:34816
	ds_read_b128 v[212:215], v163 offset:35840
	ds_read_b128 v[216:219], v163 offset:36864
	ds_read_b128 v[220:223], v163 offset:37888
	ds_read_b128 v[224:227], v163 offset:38912
	ds_read_b128 v[228:231], v163 offset:39936
	global_load_lds_dwordx4 v[236:237], off
	v_lshl_add_u64 v[236:237], s[12:13], 0, v[132:133]
	s_mov_b32 m0, s26
	s_nop 0
	global_load_lds_dwordx4 v[236:237], off
	s_waitcnt vmcnt(8)
	s_waitcnt lgkmcnt(0)
	s_barrier
	s_setprio 1
	s_waitcnt lgkmcnt(0)
	v_mfma_f32_16x16x32_bf16 v[126:129], v[164:167], v[200:203], v[126:129]
	v_mfma_f32_16x16x32_bf16 v[118:121], v[172:175], v[200:203], v[118:121]
	v_mfma_f32_16x16x32_bf16 v[110:113], v[164:167], v[208:211], v[110:113]
	v_mfma_f32_16x16x32_bf16 v[102:105], v[172:175], v[208:211], v[102:105]
	v_mfma_f32_16x16x32_bf16 v[94:97], v[164:167], v[216:219], v[94:97]
	v_mfma_f32_16x16x32_bf16 v[86:89], v[172:175], v[216:219], v[86:89]
	v_mfma_f32_16x16x32_bf16 v[78:81], v[164:167], v[224:227], v[78:81]
	v_mfma_f32_16x16x32_bf16 v[70:73], v[172:175], v[224:227], v[70:73]
	v_mfma_f32_16x16x32_bf16 v[126:129], v[168:171], v[204:207], v[126:129]
	v_mfma_f32_16x16x32_bf16 v[118:121], v[176:179], v[204:207], v[118:121]
	v_mfma_f32_16x16x32_bf16 v[110:113], v[168:171], v[212:215], v[110:113]
	v_mfma_f32_16x16x32_bf16 v[102:105], v[176:179], v[212:215], v[102:105]
	v_mfma_f32_16x16x32_bf16 v[94:97], v[168:171], v[220:223], v[94:97]
	v_mfma_f32_16x16x32_bf16 v[86:89], v[176:179], v[220:223], v[86:89]
	v_mfma_f32_16x16x32_bf16 v[78:81], v[168:171], v[228:231], v[78:81]
	v_mfma_f32_16x16x32_bf16 v[70:73], v[176:179], v[228:231], v[70:73]
	s_setprio 0
	s_setprio 1
	v_mfma_f32_16x16x32_bf16 v[122:125], v[184:187], v[200:203], v[122:125]
	v_mfma_f32_16x16x32_bf16 v[114:117], v[192:195], v[200:203], v[114:117]
	v_mfma_f32_16x16x32_bf16 v[106:109], v[184:187], v[208:211], v[106:109]
	v_mfma_f32_16x16x32_bf16 v[98:101], v[192:195], v[208:211], v[98:101]
	v_mfma_f32_16x16x32_bf16 v[90:93], v[184:187], v[216:219], v[90:93]
	v_mfma_f32_16x16x32_bf16 v[82:85], v[192:195], v[216:219], v[82:85]
	v_mfma_f32_16x16x32_bf16 v[74:77], v[184:187], v[224:227], v[74:77]
	v_mfma_f32_16x16x32_bf16 v[66:69], v[192:195], v[224:227], v[66:69]
	v_mfma_f32_16x16x32_bf16 v[122:125], v[188:191], v[204:207], v[122:125]
	v_mfma_f32_16x16x32_bf16 v[114:117], v[196:199], v[204:207], v[114:117]
	v_mfma_f32_16x16x32_bf16 v[106:109], v[188:191], v[212:215], v[106:109]
	v_mfma_f32_16x16x32_bf16 v[98:101], v[196:199], v[212:215], v[98:101]
	v_mfma_f32_16x16x32_bf16 v[90:93], v[188:191], v[220:223], v[90:93]
	v_mfma_f32_16x16x32_bf16 v[82:85], v[196:199], v[220:223], v[82:85]
	v_mfma_f32_16x16x32_bf16 v[74:77], v[188:191], v[228:231], v[74:77]
	v_mfma_f32_16x16x32_bf16 v[66:69], v[196:199], v[228:231], v[66:69]
	s_setprio 0
	s_barrier
; __device__ __forceinline__ u32x4 pack8(const float (&o)[8]) { u32x4 r; r.x = pk2(o[0], o[1]); r.y = pk2(o[2], o[3]); r.z = pk2(o[4], o[5]); r.w = pk2(o[6], o[7]); return r; }
; __device__ __forceinline__ float silu_f(float v) { return v * __builtin_amdgcn_rcpf(1.f + __expf(-v)); }
; #define PG8_STAGE(bufoff, gbase, voff) do { _Pragma("unroll") for (int _i = 0; _i < 2; ++_i) \
;         __builtin_amdgcn_global_load_lds((const unsigned*)((const char*)(gbase) + (voff)[_i]), (LAS unsigned*)(lds + (bufoff) + ldsw + _i * 8192), 16, 0, 0); } while (0)
; #define PG8_LDA(dst, b, h) do { _Pragma("unroll") for (int m = 0; m < 4; ++m) _Pragma("unroll") for (int k = 0; k < 2; ++k) dst[m][k] = *(const LAS bf16x8*)(lds + PG8_SA(b, h) + aoff + m * 2048 + k * 1024); } while (0)
; #define PG8_MMA(ai, bj, At, Bt) do { __builtin_amdgcn_s_setprio(1); _Pragma("unroll") for (int m = 0; m < 4; ++m) _Pragma("unroll") for (int n = 0; n < 2; ++n) _Pragma("unroll") for (int k = 0; k < 2; ++k) \
;         acc[ai][bj][m][n] = __builtin_amdgcn_mfma_f32_16x16x32_bf16(Bt[n][k], At[m][k], acc[ai][bj][m][n], 0, 0, 0); __builtin_amdgcn_s_setprio(0); } while (0)
; template <class Epi, bool ALIGN_EPI = PG8_ALIGN, bool SP2 = PG8_SP2>
; __device__ __forceinline__ void gemm_phase(LAS uchar* lds, const Gemm g, const StaticOrder& S, const Epi& E) {
;     ...
;             PG8_LDA(At, 1, 1); PG8_STAGE(PG8_SB(1, 0), b3, voffB); PG8_STAGE(PG8_SB(1, 1), b3 + hstepB, voffB); PG8_STAGE(PG8_SA(1, 0), a3, voffA);
;             PG8_WAIT_V(8); PG8_WAIT_L(0); PG8_BAR; PG8_MMA(1, 0, At, B0); PG8_MMA(1, 1, At, B1); PG8_BAR; PG8_SCHED;
;     ...
;         if constexpr (ALIGN_EPI) { if (wr == 0) PG8_BAR; }
;     __device__ __forceinline__ void operator()(const f32x4 (&acc)[2][2][4][2], const pg8::Unit& u, int wr, int wc, int fr, int fq, int) const {
;         const int row0 = u.pm * 256 + wr * 64 + fr, col0 = u.pn * 128 + wc * 32 + 8 * fq;
; #pragma unroll
;         for (int ai = 0; ai < 2; ++ai)
; #pragma unroll
;             for (int m = 0; m < 4; ++m) { bf16_t* rowp = O + (size_t)(row0 + ai * 128 + m * 16) * DFF + col0;
;                 float r[8];
; #pragma unroll
;                 for (int n = 0; n < 2; ++n)
; #pragma unroll
;                     for (int i = 0; i < 4; ++i) { const float gt = acc[ai][0][m][n][i], up = acc[ai][1][m][n][i]; r[n * 4 + i] = silu_f(gt) * up; }
;                 *(u32x4*)rowp = pack8(r); }
;     }
	s_add_i32 s12, s39, s21
	v_lshl_add_u64 v[160:161], v[160:161], 0, s[84:85]
	s_mov_b32 m0, s12
	ds_read_b128 v[200:203], v163 offset:49152
	ds_read_b128 v[204:207], v163 offset:50176
	ds_read_b128 v[208:211], v163 offset:51200
	ds_read_b128 v[212:215], v163 offset:52224
	ds_read_b128 v[216:219], v163 offset:53248
	ds_read_b128 v[220:223], v163 offset:54272
	ds_read_b128 v[224:227], v163 offset:55296
	ds_read_b128 v[228:231], v163 offset:56320
	global_load_lds_dwordx4 v[160:161], off
	s_add_i32 m0, s12, 0x2000
	s_add_u32 s12, s16, 0x44080
	v_lshl_add_u64 v[160:161], v[180:181], 0, s[84:85]
	s_addc_u32 s13, s17, 0
	s_add_i32 s16, s40, s21
	global_load_lds_dwordx4 v[160:161], off
	v_lshl_add_u64 v[160:161], s[12:13], 0, v[134:135]
	s_mov_b32 m0, s16
	s_nop 0
	global_load_lds_dwordx4 v[160:161], off
	v_lshl_add_u64 v[160:161], s[12:13], 0, v[130:131]
	s_add_i32 m0, s16, 0x2000
	s_nop 0
	global_load_lds_dwordx4 v[160:161], off
	v_lshl_add_u64 v[160:161], v[232:233], 0, s[84:85]
	s_mov_b32 m0, s27
	s_nop 0
	global_load_lds_dwordx4 v[160:161], off
	v_lshl_add_u64 v[160:161], v[234:235], 0, s[84:85]
	s_mov_b32 m0, s28
	s_nop 0
	global_load_lds_dwordx4 v[160:161], off
	s_waitcnt vmcnt(8)
	s_waitcnt lgkmcnt(0)
	s_barrier
	s_setprio 1
	s_waitcnt lgkmcnt(0)
	v_mfma_f32_16x16x32_bf16 v[62:65], v[164:167], v[200:203], v[62:65]
	v_mfma_f32_16x16x32_bf16 v[54:57], v[172:175], v[200:203], v[54:57]
	v_mfma_f32_16x16x32_bf16 v[46:49], v[164:167], v[208:211], v[46:49]
	v_mfma_f32_16x16x32_bf16 v[38:41], v[172:175], v[208:211], v[38:41]
	v_mfma_f32_16x16x32_bf16 v[30:33], v[164:167], v[216:219], v[30:33]
	v_mfma_f32_16x16x32_bf16 v[22:25], v[172:175], v[216:219], v[22:25]
	v_mfma_f32_16x16x32_bf16 v[14:17], v[164:167], v[224:227], v[14:17]
	v_mfma_f32_16x16x32_bf16 v[6:9], v[172:175], v[224:227], v[6:9]
	v_mfma_f32_16x16x32_bf16 v[62:65], v[168:171], v[204:207], v[62:65]
	v_mfma_f32_16x16x32_bf16 v[54:57], v[176:179], v[204:207], v[54:57]
	v_mfma_f32_16x16x32_bf16 v[46:49], v[168:171], v[212:215], v[46:49]
	v_mfma_f32_16x16x32_bf16 v[38:41], v[176:179], v[212:215], v[38:41]
	v_mfma_f32_16x16x32_bf16 v[30:33], v[168:171], v[220:223], v[30:33]
	v_mfma_f32_16x16x32_bf16 v[22:25], v[176:179], v[220:223], v[22:25]
	v_mfma_f32_16x16x32_bf16 v[14:17], v[168:171], v[228:231], v[14:17]
	v_mfma_f32_16x16x32_bf16 v[6:9], v[176:179], v[228:231], v[6:9]
	s_setprio 0
	s_setprio 1
	v_mfma_f32_16x16x32_bf16 v[58:61], v[184:187], v[200:203], v[58:61]
	v_mfma_f32_16x16x32_bf16 v[50:53], v[192:195], v[200:203], v[50:53]
	v_mfma_f32_16x16x32_bf16 v[42:45], v[184:187], v[208:211], v[42:45]
	v_mfma_f32_16x16x32_bf16 v[34:37], v[192:195], v[208:211], v[34:37]
	v_mfma_f32_16x16x32_bf16 v[26:29], v[184:187], v[216:219], v[26:29]
	v_mfma_f32_16x16x32_bf16 v[18:21], v[192:195], v[216:219], v[18:21]
	v_mfma_f32_16x16x32_bf16 v[10:13], v[184:187], v[224:227], v[10:13]
	v_mfma_f32_16x16x32_bf16 v[2:5], v[192:195], v[224:227], v[2:5]
	v_mfma_f32_16x16x32_bf16 v[58:61], v[188:191], v[204:207], v[58:61]
	v_mfma_f32_16x16x32_bf16 v[50:53], v[196:199], v[204:207], v[50:53]
	v_mfma_f32_16x16x32_bf16 v[42:45], v[188:191], v[212:215], v[42:45]
	v_mfma_f32_16x16x32_bf16 v[34:37], v[196:199], v[212:215], v[34:37]
	v_mfma_f32_16x16x32_bf16 v[26:29], v[188:191], v[220:223], v[26:29]
	v_mfma_f32_16x16x32_bf16 v[18:21], v[196:199], v[220:223], v[18:21]
	v_mfma_f32_16x16x32_bf16 v[10:13], v[188:191], v[228:231], v[10:13]
	v_mfma_f32_16x16x32_bf16 v[2:5], v[196:199], v[228:231], v[2:5]
	s_setprio 0
	s_barrier
	s_add_i32 s38, s38, 2
	s_add_u32 s36, s36, 0x100
	s_addc_u32 s37, s37, 0
	s_cmp_gt_u32 s38, 13
	s_mov_b64 s[12:13], s[14:15]
	s_cbranch_scc0 .LBB0_1050
	s_and_b64 vcc, exec, s[8:9]
	s_cbranch_vccz .LBB0_1053
	s_barrier
.LBB0_1053:
	v_lshl_or_b32 v166, s35, 7, v162
	v_lshl_add_u32 v164, s34, 8, v1
	v_mov_b32_e32 v252, 0xbfb8aa3b
	v_mov_b32_e32 v253, 0xbfb8aa3b
	v_ashrrev_i32_e32 v167, 31, v166
	v_mov_b64_e32 v[160:161], s[90:91]
	v_mov_b32_e32 v250, 1.0
	v_mov_b32_e32 v251, 1.0
	v_lshlrev_b64 v[166:167], 1, v[166:167]
	s_and_b64 vcc, exec, s[4:5]
	v_lshl_add_u64 v[160:161], v[160:161], 0, v[166:167]
	v_mad_i64_i32 v[200:201], s[12:13], v164, s80, v[160:161]
	v_pk_mul_f32 v[122:123], v[126:127], v[122:123]
	v_pk_mul_f32 v[124:125], v[128:129], v[124:125]
	v_pk_mul_f32 v[114:115], v[118:119], v[114:115]
	v_pk_mul_f32 v[116:117], v[120:121], v[116:117]
	v_pk_mul_f32 v[126:127], v[126:127], v[252:253]
	v_pk_mul_f32 v[128:129], v[128:129], v[252:253]
	v_pk_mul_f32 v[118:119], v[118:119], v[252:253]
	v_pk_mul_f32 v[120:121], v[120:121], v[252:253]
	v_exp_f32_e32 v126, v126
	v_exp_f32_e32 v127, v127
	v_exp_f32_e32 v128, v128
	v_exp_f32_e32 v129, v129
	v_exp_f32_e32 v118, v118
	v_exp_f32_e32 v119, v119
	v_exp_f32_e32 v120, v120
	v_exp_f32_e32 v121, v121
	v_pk_add_f32 v[126:127], v[126:127], v[250:251]
	v_pk_add_f32 v[128:129], v[128:129], v[250:251]
	v_pk_add_f32 v[118:119], v[118:119], v[250:251]
	v_pk_add_f32 v[120:121], v[120:121], v[250:251]
	v_rcp_f32_e32 v126, v126
	v_rcp_f32_e32 v127, v127
	v_rcp_f32_e32 v128, v128
	v_rcp_f32_e32 v129, v129
	v_rcp_f32_e32 v118, v118
	v_rcp_f32_e32 v119, v119
	v_rcp_f32_e32 v120, v120
	v_rcp_f32_e32 v121, v121
	v_pk_mul_f32 v[122:123], v[122:123], v[126:127]
	v_pk_mul_f32 v[124:125], v[124:125], v[128:129]
	v_pk_mul_f32 v[114:115], v[114:115], v[118:119]
	v_pk_mul_f32 v[116:117], v[116:117], v[120:121]
	v_cvt_pk_bf16_f32 v230, v122, v123
	v_cvt_pk_bf16_f32 v231, v124, v125
	v_cvt_pk_bf16_f32 v232, v114, v115
	v_cvt_pk_bf16_f32 v233, v116, v117
	global_store_dwordx4 v[200:201], v[230:233], off
	v_add_u32_e32 v221, 16, v164
	v_mad_i64_i32 v[202:203], s[12:13], v221, s80, v[160:161]
; __device__ __forceinline__ u32x4 pack8(const float (&o)[8]) { u32x4 r; r.x = pk2(o[0], o[1]); r.y = pk2(o[2], o[3]); r.z = pk2(o[4], o[5]); r.w = pk2(o[6], o[7]); return r; }
; __device__ __forceinline__ float silu_f(float v) { return v * __builtin_amdgcn_rcpf(1.f + __expf(-v)); }
;     __device__ __forceinline__ void operator()(const f32x4 (&acc)[2][2][4][2], const pg8::Unit& u, int wr, int wc, int fr, int fq, int) const {
;         const int row0 = u.pm * 256 + wr * 64 + fr, col0 = u.pn * 128 + wc * 32 + 8 * fq;
; #pragma unroll
;         for (int ai = 0; ai < 2; ++ai)
; #pragma unroll
;             for (int m = 0; m < 4; ++m) { bf16_t* rowp = O + (size_t)(row0 + ai * 128 + m * 16) * DFF + col0;
;                 float r[8];
; #pragma unroll
;                 for (int n = 0; n < 2; ++n)
; #pragma unroll
;                     for (int i = 0; i < 4; ++i) { const float gt = acc[ai][0][m][n][i], up = acc[ai][1][m][n][i]; r[n * 4 + i] = silu_f(gt) * up; }
;                 *(u32x4*)rowp = pack8(r); }
;     }
	v_pk_mul_f32 v[106:107], v[110:111], v[106:107]
	v_pk_mul_f32 v[108:109], v[112:113], v[108:109]
	v_pk_mul_f32 v[98:99], v[102:103], v[98:99]
	v_pk_mul_f32 v[100:101], v[104:105], v[100:101]
	v_pk_mul_f32 v[110:111], v[110:111], v[252:253]
	v_pk_mul_f32 v[112:113], v[112:113], v[252:253]
	v_pk_mul_f32 v[102:103], v[102:103], v[252:253]
	v_pk_mul_f32 v[104:105], v[104:105], v[252:253]
	v_exp_f32_e32 v110, v110
	v_exp_f32_e32 v111, v111
	v_exp_f32_e32 v112, v112
	v_exp_f32_e32 v113, v113
	v_exp_f32_e32 v102, v102
	v_exp_f32_e32 v103, v103
	v_exp_f32_e32 v104, v104
	v_exp_f32_e32 v105, v105
	v_pk_add_f32 v[110:111], v[110:111], v[250:251]
	v_pk_add_f32 v[112:113], v[112:113], v[250:251]
	v_pk_add_f32 v[102:103], v[102:103], v[250:251]
	v_pk_add_f32 v[104:105], v[104:105], v[250:251]
	v_rcp_f32_e32 v110, v110
	v_rcp_f32_e32 v111, v111
	v_rcp_f32_e32 v112, v112
	v_rcp_f32_e32 v113, v113
	v_rcp_f32_e32 v102, v102
	v_rcp_f32_e32 v103, v103
	v_rcp_f32_e32 v104, v104
	v_rcp_f32_e32 v105, v105
	v_pk_mul_f32 v[106:107], v[106:107], v[110:111]
	v_pk_mul_f32 v[108:109], v[108:109], v[112:113]
	v_pk_mul_f32 v[98:99], v[98:99], v[102:103]
	v_pk_mul_f32 v[100:101], v[100:101], v[104:105]
	v_cvt_pk_bf16_f32 v234, v106, v107
	v_cvt_pk_bf16_f32 v235, v108, v109
	v_cvt_pk_bf16_f32 v236, v98, v99
	v_cvt_pk_bf16_f32 v237, v100, v101
	global_store_dwordx4 v[202:203], v[234:237], off
	v_add_u32_e32 v222, 32, v164
	v_mad_i64_i32 v[204:205], s[12:13], v222, s80, v[160:161]
	v_pk_mul_f32 v[90:91], v[94:95], v[90:91]
	v_pk_mul_f32 v[92:93], v[96:97], v[92:93]
	v_pk_mul_f32 v[82:83], v[86:87], v[82:83]
	v_pk_mul_f32 v[84:85], v[88:89], v[84:85]
	v_pk_mul_f32 v[94:95], v[94:95], v[252:253]
	v_pk_mul_f32 v[96:97], v[96:97], v[252:253]
	v_pk_mul_f32 v[86:87], v[86:87], v[252:253]
	v_pk_mul_f32 v[88:89], v[88:89], v[252:253]
	v_exp_f32_e32 v94, v94
	v_exp_f32_e32 v95, v95
	v_exp_f32_e32 v96, v96
	v_exp_f32_e32 v97, v97
	v_exp_f32_e32 v86, v86
	v_exp_f32_e32 v87, v87
	v_exp_f32_e32 v88, v88
	v_exp_f32_e32 v89, v89
	v_pk_add_f32 v[94:95], v[94:95], v[250:251]
	v_pk_add_f32 v[96:97], v[96:97], v[250:251]
	v_pk_add_f32 v[86:87], v[86:87], v[250:251]
	v_pk_add_f32 v[88:89], v[88:89], v[250:251]
	v_rcp_f32_e32 v94, v94
	v_rcp_f32_e32 v95, v95
	v_rcp_f32_e32 v96, v96
	v_rcp_f32_e32 v97, v97
	v_rcp_f32_e32 v86, v86
	v_rcp_f32_e32 v87, v87
	v_rcp_f32_e32 v88, v88
	v_rcp_f32_e32 v89, v89
	v_pk_mul_f32 v[90:91], v[90:91], v[94:95]
	v_pk_mul_f32 v[92:93], v[92:93], v[96:97]
	v_pk_mul_f32 v[82:83], v[82:83], v[86:87]
	v_pk_mul_f32 v[84:85], v[84:85], v[88:89]
	v_cvt_pk_bf16_f32 v238, v90, v91
	v_cvt_pk_bf16_f32 v239, v92, v93
	v_cvt_pk_bf16_f32 v240, v82, v83
	v_cvt_pk_bf16_f32 v241, v84, v85
	global_store_dwordx4 v[204:205], v[238:241], off
	v_add_u32_e32 v223, 48, v164
	v_mad_i64_i32 v[206:207], s[12:13], v223, s80, v[160:161]
	v_pk_mul_f32 v[74:75], v[78:79], v[74:75]
	v_pk_mul_f32 v[76:77], v[80:81], v[76:77]
	v_pk_mul_f32 v[66:67], v[70:71], v[66:67]
	v_pk_mul_f32 v[68:69], v[72:73], v[68:69]
	v_pk_mul_f32 v[78:79], v[78:79], v[252:253]
	v_pk_mul_f32 v[80:81], v[80:81], v[252:253]
	v_pk_mul_f32 v[70:71], v[70:71], v[252:253]
	v_pk_mul_f32 v[72:73], v[72:73], v[252:253]
	v_exp_f32_e32 v78, v78
	v_exp_f32_e32 v79, v79
	v_exp_f32_e32 v80, v80
	v_exp_f32_e32 v81, v81
	v_exp_f32_e32 v70, v70
	v_exp_f32_e32 v71, v71
	v_exp_f32_e32 v72, v72
	v_exp_f32_e32 v73, v73
	v_pk_add_f32 v[78:79], v[78:79], v[250:251]
	v_pk_add_f32 v[80:81], v[80:81], v[250:251]
	v_pk_add_f32 v[70:71], v[70:71], v[250:251]
	v_pk_add_f32 v[72:73], v[72:73], v[250:251]
	v_rcp_f32_e32 v78, v78
	v_rcp_f32_e32 v79, v79
	v_rcp_f32_e32 v80, v80
	v_rcp_f32_e32 v81, v81
	v_rcp_f32_e32 v70, v70
	v_rcp_f32_e32 v71, v71
	v_rcp_f32_e32 v72, v72
	v_rcp_f32_e32 v73, v73
	v_pk_mul_f32 v[74:75], v[74:75], v[78:79]
	v_pk_mul_f32 v[76:77], v[76:77], v[80:81]
	v_pk_mul_f32 v[66:67], v[66:67], v[70:71]
	v_pk_mul_f32 v[68:69], v[68:69], v[72:73]
	v_cvt_pk_bf16_f32 v242, v74, v75
	v_cvt_pk_bf16_f32 v243, v76, v77
	v_cvt_pk_bf16_f32 v244, v66, v67
	v_cvt_pk_bf16_f32 v245, v68, v69
	global_store_dwordx4 v[206:207], v[242:245], off
	v_add_u32_e32 v224, 128, v164
	v_mad_i64_i32 v[208:209], s[12:13], v224, s80, v[160:161]
	v_pk_mul_f32 v[58:59], v[62:63], v[58:59]
	v_pk_mul_f32 v[60:61], v[64:65], v[60:61]
	v_pk_mul_f32 v[50:51], v[54:55], v[50:51]
	v_pk_mul_f32 v[52:53], v[56:57], v[52:53]
	v_pk_mul_f32 v[62:63], v[62:63], v[252:253]
	v_pk_mul_f32 v[64:65], v[64:65], v[252:253]
	v_pk_mul_f32 v[54:55], v[54:55], v[252:253]
	v_pk_mul_f32 v[56:57], v[56:57], v[252:253]
	v_exp_f32_e32 v62, v62
	v_exp_f32_e32 v63, v63
	v_exp_f32_e32 v64, v64
	v_exp_f32_e32 v65, v65
	v_exp_f32_e32 v54, v54
	v_exp_f32_e32 v55, v55
	v_exp_f32_e32 v56, v56
	v_exp_f32_e32 v57, v57
	v_pk_add_f32 v[62:63], v[62:63], v[250:251]
	v_pk_add_f32 v[64:65], v[64:65], v[250:251]
; __device__ __forceinline__ u32x4 pack8(const float (&o)[8]) { u32x4 r; r.x = pk2(o[0], o[1]); r.y = pk2(o[2], o[3]); r.z = pk2(o[4], o[5]); r.w = pk2(o[6], o[7]); return r; }
; __device__ __forceinline__ float silu_f(float v) { return v * __builtin_amdgcn_rcpf(1.f + __expf(-v)); }
; #define PG8_BAR __builtin_amdgcn_s_barrier()
; template <class Epi, bool ALIGN_EPI = PG8_ALIGN, bool SP2 = PG8_SP2>
; __device__ __forceinline__ void gemm_phase(LAS uchar* lds, const Gemm g, const StaticOrder& S, const Epi& E) {
;     ...
;         E(acc, cur, wr, wc, fr, fq, ui);
;         if (!has_next) break;
; #pragma unroll
;         for (int a = 0; a < 2; ++a)
; #pragma unroll
;             for (int b = 0; b < 2; ++b)
; #pragma unroll
;                 for (int m = 0; m < 4; ++m)
; #pragma unroll
;                     for (int n = 0; n < 2; ++n) acc[a][b][m][n] = (f32x4){0.f, 0.f, 0.f, 0.f};
;         cur = nxt; cA = nA; cB = nB; ++ui;
;         if constexpr (ALIGN_EPI) { if (wr == 1) PG8_BAR; }
;     __device__ __forceinline__ void operator()(const f32x4 (&acc)[2][2][4][2], const pg8::Unit& u, int wr, int wc, int fr, int fq, int) const {
;         const int row0 = u.pm * 256 + wr * 64 + fr, col0 = u.pn * 128 + wc * 32 + 8 * fq;
; #pragma unroll
;         for (int ai = 0; ai < 2; ++ai)
; #pragma unroll
;             for (int m = 0; m < 4; ++m) { bf16_t* rowp = O + (size_t)(row0 + ai * 128 + m * 16) * DFF + col0;
;                 float r[8];
; #pragma unroll
;                 for (int n = 0; n < 2; ++n)
; #pragma unroll
;                     for (int i = 0; i < 4; ++i) { const float gt = acc[ai][0][m][n][i], up = acc[ai][1][m][n][i]; r[n * 4 + i] = silu_f(gt) * up; }
;                 *(u32x4*)rowp = pack8(r); }
;     }
	v_pk_add_f32 v[54:55], v[54:55], v[250:251]
	v_pk_add_f32 v[56:57], v[56:57], v[250:251]
	v_rcp_f32_e32 v62, v62
	v_rcp_f32_e32 v63, v63
	v_rcp_f32_e32 v64, v64
	v_rcp_f32_e32 v65, v65
	v_rcp_f32_e32 v54, v54
	v_rcp_f32_e32 v55, v55
	v_rcp_f32_e32 v56, v56
	v_rcp_f32_e32 v57, v57
	v_pk_mul_f32 v[58:59], v[58:59], v[62:63]
	v_pk_mul_f32 v[60:61], v[60:61], v[64:65]
	v_pk_mul_f32 v[50:51], v[50:51], v[54:55]
	v_pk_mul_f32 v[52:53], v[52:53], v[56:57]
	v_cvt_pk_bf16_f32 v230, v58, v59
	v_cvt_pk_bf16_f32 v231, v60, v61
	v_cvt_pk_bf16_f32 v232, v50, v51
	v_cvt_pk_bf16_f32 v233, v52, v53
	global_store_dwordx4 v[208:209], v[230:233], off
	v_add_u32_e32 v225, 144, v164
	v_mad_i64_i32 v[210:211], s[12:13], v225, s80, v[160:161]
	v_pk_mul_f32 v[42:43], v[46:47], v[42:43]
	v_pk_mul_f32 v[44:45], v[48:49], v[44:45]
	v_pk_mul_f32 v[34:35], v[38:39], v[34:35]
	v_pk_mul_f32 v[36:37], v[40:41], v[36:37]
	v_pk_mul_f32 v[46:47], v[46:47], v[252:253]
	v_pk_mul_f32 v[48:49], v[48:49], v[252:253]
	v_pk_mul_f32 v[38:39], v[38:39], v[252:253]
	v_pk_mul_f32 v[40:41], v[40:41], v[252:253]
	v_exp_f32_e32 v46, v46
	v_exp_f32_e32 v47, v47
	v_exp_f32_e32 v48, v48
	v_exp_f32_e32 v49, v49
	v_exp_f32_e32 v38, v38
	v_exp_f32_e32 v39, v39
	v_exp_f32_e32 v40, v40
	v_exp_f32_e32 v41, v41
	v_pk_add_f32 v[46:47], v[46:47], v[250:251]
	v_pk_add_f32 v[48:49], v[48:49], v[250:251]
	v_pk_add_f32 v[38:39], v[38:39], v[250:251]
	v_pk_add_f32 v[40:41], v[40:41], v[250:251]
	v_rcp_f32_e32 v46, v46
	v_rcp_f32_e32 v47, v47
	v_rcp_f32_e32 v48, v48
	v_rcp_f32_e32 v49, v49
	v_rcp_f32_e32 v38, v38
	v_rcp_f32_e32 v39, v39
	v_rcp_f32_e32 v40, v40
	v_rcp_f32_e32 v41, v41
	v_pk_mul_f32 v[42:43], v[42:43], v[46:47]
	v_pk_mul_f32 v[44:45], v[44:45], v[48:49]
	v_pk_mul_f32 v[34:35], v[34:35], v[38:39]
	v_pk_mul_f32 v[36:37], v[36:37], v[40:41]
	v_cvt_pk_bf16_f32 v234, v42, v43
	v_cvt_pk_bf16_f32 v235, v44, v45
	v_cvt_pk_bf16_f32 v236, v34, v35
	v_cvt_pk_bf16_f32 v237, v36, v37
	global_store_dwordx4 v[210:211], v[234:237], off
	v_add_u32_e32 v226, 160, v164
	v_mad_i64_i32 v[212:213], s[12:13], v226, s80, v[160:161]
	v_pk_mul_f32 v[26:27], v[30:31], v[26:27]
	v_pk_mul_f32 v[28:29], v[32:33], v[28:29]
	v_pk_mul_f32 v[18:19], v[22:23], v[18:19]
	v_pk_mul_f32 v[20:21], v[24:25], v[20:21]
	v_pk_mul_f32 v[30:31], v[30:31], v[252:253]
	v_pk_mul_f32 v[32:33], v[32:33], v[252:253]
	v_pk_mul_f32 v[22:23], v[22:23], v[252:253]
	v_pk_mul_f32 v[24:25], v[24:25], v[252:253]
	v_exp_f32_e32 v30, v30
	v_exp_f32_e32 v31, v31
	v_exp_f32_e32 v32, v32
	v_exp_f32_e32 v33, v33
	v_exp_f32_e32 v22, v22
	v_exp_f32_e32 v23, v23
	v_exp_f32_e32 v24, v24
	v_exp_f32_e32 v25, v25
	v_pk_add_f32 v[30:31], v[30:31], v[250:251]
	v_pk_add_f32 v[32:33], v[32:33], v[250:251]
	v_pk_add_f32 v[22:23], v[22:23], v[250:251]
	v_pk_add_f32 v[24:25], v[24:25], v[250:251]
	v_rcp_f32_e32 v30, v30
	v_rcp_f32_e32 v31, v31
	v_rcp_f32_e32 v32, v32
	v_rcp_f32_e32 v33, v33
	v_rcp_f32_e32 v22, v22
	v_rcp_f32_e32 v23, v23
	v_rcp_f32_e32 v24, v24
	v_rcp_f32_e32 v25, v25
	v_pk_mul_f32 v[26:27], v[26:27], v[30:31]
	v_pk_mul_f32 v[28:29], v[28:29], v[32:33]
	v_pk_mul_f32 v[18:19], v[18:19], v[22:23]
	v_pk_mul_f32 v[20:21], v[20:21], v[24:25]
	v_cvt_pk_bf16_f32 v238, v26, v27
	v_cvt_pk_bf16_f32 v239, v28, v29
	v_cvt_pk_bf16_f32 v240, v18, v19
	v_cvt_pk_bf16_f32 v241, v20, v21
	global_store_dwordx4 v[212:213], v[238:241], off
	v_add_u32_e32 v227, 176, v164
	v_mad_i64_i32 v[214:215], s[12:13], v227, s80, v[160:161]
	v_pk_mul_f32 v[10:11], v[14:15], v[10:11]
	v_pk_mul_f32 v[12:13], v[16:17], v[12:13]
	v_pk_mul_f32 v[2:3], v[6:7], v[2:3]
	v_pk_mul_f32 v[4:5], v[8:9], v[4:5]
	v_pk_mul_f32 v[14:15], v[14:15], v[252:253]
	v_pk_mul_f32 v[16:17], v[16:17], v[252:253]
	v_pk_mul_f32 v[6:7], v[6:7], v[252:253]
	v_pk_mul_f32 v[8:9], v[8:9], v[252:253]
	v_exp_f32_e32 v14, v14
	v_exp_f32_e32 v15, v15
	v_exp_f32_e32 v16, v16
	v_exp_f32_e32 v17, v17
	v_exp_f32_e32 v6, v6
	v_exp_f32_e32 v7, v7
	v_exp_f32_e32 v8, v8
	v_exp_f32_e32 v9, v9
	v_pk_add_f32 v[14:15], v[14:15], v[250:251]
	v_pk_add_f32 v[16:17], v[16:17], v[250:251]
	v_pk_add_f32 v[6:7], v[6:7], v[250:251]
	v_pk_add_f32 v[8:9], v[8:9], v[250:251]
	v_rcp_f32_e32 v14, v14
	v_rcp_f32_e32 v15, v15
	v_rcp_f32_e32 v16, v16
	v_rcp_f32_e32 v17, v17
	v_rcp_f32_e32 v6, v6
	v_rcp_f32_e32 v7, v7
	v_rcp_f32_e32 v8, v8
	v_rcp_f32_e32 v9, v9
	v_pk_mul_f32 v[10:11], v[10:11], v[14:15]
	v_pk_mul_f32 v[12:13], v[12:13], v[16:17]
	v_pk_mul_f32 v[2:3], v[2:3], v[6:7]
	v_pk_mul_f32 v[4:5], v[4:5], v[8:9]
	v_cvt_pk_bf16_f32 v242, v10, v11
	v_cvt_pk_bf16_f32 v243, v12, v13
	v_cvt_pk_bf16_f32 v244, v2, v3
	v_cvt_pk_bf16_f32 v245, v4, v5
	global_store_dwordx4 v[214:215], v[242:245], off
	s_mov_b64 s[12:13], -1
	s_cbranch_vccnz .LBB0_1042
	s_andn2_b64 vcc, exec, s[6:7]
	s_cbranch_vccnz .LBB0_1041
	s_barrier
	s_branch .LBB0_1041
